# phase prologue: kernel-argument reloads batched (five scalar-load round trips -> three)
# baseline (speedup 1.0000x reference)
.LBB0_22:
	v_readlane_b32 s0, v252, 1
	v_mov_b32_e32 v237, v185
	v_readlane_b32 s1, v252, 2
	s_load_dwordx16 s[36:51], s[0:1], 0x0
	s_load_dwordx2 s[4:5], s[0:1], 0x70
	s_load_dwordx4 s[8:11], s[0:1], 0x60
	v_lshl_add_u32 v239, s95, 6, v237
	s_mov_b32 s65, s71
	v_and_b32_e32 v238, 63, v237
	s_waitcnt lgkmcnt(0)
	v_writelane_b32 v253, s4, 19
	s_nop 1
	v_writelane_b32 v253, s5, 20
	v_writelane_b32 v253, s8, 21
	v_writelane_b32 v253, s9, 22
	v_writelane_b32 v253, s10, 23
	v_writelane_b32 v253, s11, 24
	s_load_dwordx8 s[4:11], s[0:1], 0x40
	s_waitcnt lgkmcnt(0)
	v_writelane_b32 v253, s4, 25
	s_nop 1
	v_writelane_b32 v253, s5, 26
	v_writelane_b32 v253, s6, 27
	v_writelane_b32 v253, s7, 28
	v_writelane_b32 v253, s8, 29
	v_writelane_b32 v253, s9, 30
	v_writelane_b32 v253, s10, 31
	v_writelane_b32 v253, s11, 32
	s_load_dwordx8 s[4:11], s[0:1], 0x98
	v_writelane_b32 v252, s0, 1
	v_writelane_b32 v252, s1, 2
	s_load_dwordx2 s[0:1], s[0:1], 0xc0
	s_waitcnt lgkmcnt(0)
	v_writelane_b32 v253, s4, 33
	s_nop 1
	v_writelane_b32 v253, s5, 34
	v_writelane_b32 v253, s6, 35
	v_writelane_b32 v253, s7, 36
	v_writelane_b32 v253, s8, 37
	v_writelane_b32 v253, s9, 38
	v_writelane_b32 v253, s10, 39
	v_writelane_b32 v253, s11, 40
	v_writelane_b32 v253, s0, 41
	s_mov_b64 s[6:7], s[26:27]
	s_nop 0
	v_writelane_b32 v253, s1, 42
	v_readlane_b32 s0, v252, 0
	s_add_i32 s97, s65, 0
	s_nop 0
	v_writelane_b32 v253, s0, 43
	v_readfirstlane_b32 s0, v239
	s_nop 1
	v_writelane_b32 v253, s0, 44
	s_ashr_i32 s0, s0, 6
	v_writelane_b32 v253, s0, 45
	s_cmp_lg_u32 s26, 0
	s_nop 0
	v_writelane_b32 v253, s1, 46
	v_writelane_b32 v253, s4, 47
	s_mov_b64 s[0:1], -1
	s_nop 0
	v_writelane_b32 v253, s5, 48
	v_writelane_b32 v253, s6, 49
	v_writelane_b32 v253, s7, 50
	s_cbranch_scc0 .LBB0_775
	v_readlane_b32 s0, v253, 41
	v_readlane_b32 s1, v253, 42
	s_add_u32 s4, s0, 0x8000000
	s_addc_u32 s5, s1, 0
	v_writelane_b32 v253, s4, 51
	s_add_u32 s0, s0, 0xc800000
	s_addc_u32 s1, s1, 0
	v_writelane_b32 v253, s5, 52
	v_writelane_b32 v253, s0, 53
	s_nop 1
	v_writelane_b32 v253, s1, 54
	s_nop 0
	v_readlane_b32 s4, v253, 47
	v_readlane_b32 s6, v253, 49
	s_add_i32 s0, s6, -2
	s_mul_hi_i32 s1, s0, 0x92492493
	s_add_i32 s1, s1, s0
	s_lshr_b32 s4, s1, 31
	s_ashr_i32 s1, s1, 2
	v_readlane_b32 s5, v253, 48
	s_add_i32 s4, s1, s4
	s_mul_i32 s1, s4, 7
	s_ashr_i32 s5, s4, 31
	v_readlane_b32 s7, v253, 50
	s_sub_i32 s80, s0, s1
	v_writelane_b32 v253, s4, 55
	s_cmp_lg_u32 s80, 3
	s_mov_b64 s[0:1], -1
	v_writelane_b32 v253, s5, 56
	s_cbranch_scc0 .LBB0_601
	v_readlane_b32 s0, v253, 41
	v_readlane_b32 s1, v253, 42
	s_add_u32 s74, s0, 0x1000000
	s_addc_u32 s75, s1, 0
	s_add_u32 s20, s0, 0x6000000
	s_addc_u32 s21, s1, 0
	s_cmp_eq_u32 s80, -1
	s_cselect_b64 s[22:23], -1, 0
	s_cmp_lg_u32 s80, -1
	s_cselect_b64 s[0:1], -1, 0
	s_mov_b64 s[4:5], -1
	s_and_b64 vcc, exec, s[0:1]
	s_cbranch_vccz .LBB0_28
	v_readlane_b32 s6, v253, 55
	s_mul_i32 s5, s6, 0x2780000
	s_mul_hi_i32 s4, s6, 0x2780000
	s_add_u32 s12, s74, s5
	s_addc_u32 s13, s75, s4
	s_cmp_lt_i32 s80, 4
	v_readlane_b32 s7, v253, 56
	s_cbranch_scc1 .LBB0_33
	s_cmp_gt_i32 s80, 4
	s_cbranch_scc0 .LBB0_570
	s_cmp_lg_u32 s80, 5
	s_mov_b64 s[4:5], -1
	s_cselect_b64 s[8:9], -1, 0
	s_cbranch_execz .LBB0_571
	s_branch .LBB0_572
